# GQA main loop: 14 redundant counted lgkmcnt waits per key tile removed (K fragments are already drained at the previous barrier; one lgkmcnt(0) for the V transpose reads)
# speedup vs baseline: 1.0017x; 1.0017x over previous
.LBB0_707:
	s_add_i32 s22, s23, 2
	v_add_u32_e32 v186, s0, v207
	ds_read_b64_tr_b16 v[178:179], v186 offset:24576
	ds_read_b64_tr_b16 v[180:181], v186 offset:25088
	v_mfma_f32_32x32x16_bf16 v[98:113], v[174:177], v[142:145], v[34:49]
	v_add_f32_e32 v82, v66, v67
	v_add_f32_e32 v82, v68, v82
	v_add_f32_e32 v82, v69, v82
	v_add_f32_e32 v82, v70, v82
	v_add_f32_e32 v82, v71, v82
	v_cvt_pk_bf16_f32 v134, v66, v67
	v_cvt_pk_bf16_f32 v135, v68, v69
	ds_read_b64_tr_b16 v[174:175], v186 offset:28672
	ds_read_b64_tr_b16 v[176:177], v186 offset:29184
	v_add_f32_e32 v66, v72, v82
	v_mfma_f32_32x32x16_bf16 v[82:97], v[170:173], v[142:145], v[34:49]
	v_add_f32_e32 v66, v73, v66
	v_add_f32_e32 v66, v74, v66
	v_add_f32_e32 v114, v75, v66
	v_cvt_pk_bf16_f32 v136, v70, v71
	v_cvt_pk_bf16_f32 v137, v72, v73
	ds_read_b64_tr_b16 v[66:67], v186 offset:25600
	ds_read_b64_tr_b16 v[68:69], v186 offset:26112
	v_mfma_f32_32x32x16_bf16 v[98:113], v[166:169], v[138:141], v[98:113]
	v_add_f32_e32 v70, v76, v114
	v_add_f32_e32 v70, v77, v70
	v_add_f32_e32 v70, v78, v70
	v_add_f32_e32 v114, v79, v70
	v_cvt_pk_bf16_f32 v126, v74, v75
	v_cvt_pk_bf16_f32 v127, v76, v77
	ds_read_b64_tr_b16 v[70:71], v186 offset:29696
	ds_read_b64_tr_b16 v[72:73], v186 offset:30208
	v_mfma_f32_32x32x16_bf16 v[82:97], v[162:165], v[138:141], v[82:97]
	v_add_f32_e32 v74, v80, v114
	v_add_f32_e32 v74, v81, v74
	v_add_f32_e32 v74, v50, v74
	v_add_f32_e32 v114, v51, v74
	v_cvt_pk_bf16_f32 v128, v78, v79
	v_cvt_pk_bf16_f32 v129, v80, v81
	ds_read_b64_tr_b16 v[74:75], v186 offset:26624
	ds_read_b64_tr_b16 v[76:77], v186 offset:27136
	v_mfma_f32_32x32x16_bf16 v[98:113], v[158:161], v[130:133], v[98:113]
	v_add_f32_e32 v78, v52, v114
	v_add_f32_e32 v78, v53, v78
	v_add_f32_e32 v78, v54, v78
	v_add_f32_e32 v78, v55, v78
	v_cvt_pk_bf16_f32 v118, v50, v51
	v_cvt_pk_bf16_f32 v119, v52, v53
	ds_read_b64_tr_b16 v[50:51], v186 offset:30720
	ds_read_b64_tr_b16 v[52:53], v186 offset:31232
	v_mfma_f32_32x32x16_bf16 v[82:97], v[154:157], v[130:133], v[82:97]
	v_add_f32_e32 v78, v56, v78
	v_add_f32_e32 v78, v57, v78
	v_add_f32_e32 v78, v58, v78
	v_add_f32_e32 v78, v59, v78
	v_cvt_pk_bf16_f32 v120, v54, v55
	v_cvt_pk_bf16_f32 v121, v56, v57
	ds_read_b64_tr_b16 v[54:55], v186 offset:27648
	ds_read_b64_tr_b16 v[56:57], v186 offset:28160
	v_mfma_f32_32x32x16_bf16 v[98:113], v[150:153], v[122:125], v[98:113]
	v_add_f32_e32 v78, v60, v78
	v_add_f32_e32 v78, v61, v78
	v_add_f32_e32 v78, v62, v78
	v_add_f32_e32 v78, v63, v78
	v_cvt_pk_bf16_f32 v114, v58, v59
	v_cvt_pk_bf16_f32 v115, v60, v61
	ds_read_b64_tr_b16 v[58:59], v186 offset:31744
	ds_read_b64_tr_b16 v[60:61], v186 offset:32256
	v_mfma_f32_32x32x16_bf16 v[82:97], v[146:149], v[122:125], v[82:97]
	v_add_f32_e32 v78, v64, v78
	v_add_f32_e32 v78, v65, v78
	v_cvt_pk_bf16_f32 v116, v62, v63
	v_cvt_pk_bf16_f32 v117, v64, v65
	s_cmpk_gt_u32 s22, 0x7c
	s_cselect_b64 s[0:1], -1, 0
	s_cmpk_lt_u32 s22, 0x7d
	s_cselect_b32 s4, 0, 0xffffff80
	s_cselect_b32 s5, s9, s20
	s_add_i32 s4, s4, s23
	s_lshl_b32 s4, s4, 6
	s_add_i32 s4, s4, s5
	s_addk_i32 s4, 0x140
	s_add_i32 m0, s24, s18
	v_mad_i64_i32 v[62:63], s[4:5], s4, v217, v[192:193]
	global_load_lds_dwordx4 v[62:63], off
	v_max_f32_e32 v62, v98, v99
	v_max3_f32 v63, v100, v101, v83
	v_max3_f32 v62, v62, v82, v84
	v_max3_f32 v62, v62, v85, v102
	v_max3_f32 v63, v63, v104, v105
	v_max3_f32 v62, v62, v103, v86
	v_max3_f32 v63, v63, v88, v89
	v_max3_f32 v62, v62, v87, v106
	v_max3_f32 v63, v63, v108, v109
	v_max3_f32 v62, v62, v107, v90
	v_max3_f32 v63, v63, v92, v93
	v_max3_f32 v62, v62, v91, v110
	v_max3_f32 v63, v63, v112, v113
	v_max3_f32 v62, v62, v111, v94
	v_max3_f32 v63, v63, v96, v97
	v_max3_f32 v62, v62, v95, v63
	v_mov_b32_e32 v63, v62
	s_add_i32 m0, s21, s19
	s_nop 0
	v_permlane32_swap_b32_e32 v62, v63
	global_load_lds_dwordx4 v[196:197], off
	v_max_f32_e32 v62, v62, v63
	v_cmp_lt_f32_e32 vcc, s51, v62
	s_cmp_lg_u64 vcc, 0
	v_add_f32_e32 v224, v224, v78
	s_cselect_b64 s[4:5], -1, 0
	s_cbranch_vccnz .LBB0_715
.LBB0_708:
	s_waitcnt lgkmcnt(0)
	v_mfma_f32_32x32x16_bf16 v[2:17], v[134:137], v[178:181], v[2:17]
	v_exp_f32_e32 v98, v98
	v_exp_f32_e32 v99, v99
	v_exp_f32_e32 v100, v100
	v_exp_f32_e32 v101, v101
	v_mfma_f32_32x32x16_bf16 v[18:33], v[134:137], v[174:177], v[18:33]
	v_exp_f32_e32 v102, v102
	v_exp_f32_e32 v103, v103
	v_exp_f32_e32 v104, v104
	v_exp_f32_e32 v105, v105
	v_add_u32_e32 v78, s21, v206
	ds_read_b128 v[62:65], v78
	ds_read_b128 v[174:177], v78 offset:512
	v_mfma_f32_32x32x16_bf16 v[2:17], v[126:129], v[66:69], v[2:17]
	v_exp_f32_e32 v106, v106
	v_exp_f32_e32 v107, v107
	v_exp_f32_e32 v108, v108
	v_exp_f32_e32 v109, v109
	ds_read_b128 v[178:181], v78 offset:2048
	ds_read_b128 v[170:173], v78 offset:2560
	v_mfma_f32_32x32x16_bf16 v[18:33], v[126:129], v[70:73], v[18:33]
	v_exp_f32_e32 v110, v110
	v_exp_f32_e32 v111, v111
	v_exp_f32_e32 v112, v112
	v_exp_f32_e32 v113, v113
	ds_read_b128 v[166:169], v78 offset:4096
	ds_read_b128 v[162:165], v78 offset:4608
	v_mfma_f32_32x32x16_bf16 v[2:17], v[118:121], v[74:77], v[2:17]
	v_exp_f32_e32 v82, v82
	v_exp_f32_e32 v83, v83
	v_exp_f32_e32 v84, v84
	v_exp_f32_e32 v85, v85
	ds_read_b128 v[158:161], v78 offset:6144
	ds_read_b128 v[154:157], v78 offset:6656
	v_mfma_f32_32x32x16_bf16 v[18:33], v[118:121], v[50:53], v[18:33]
	v_exp_f32_e32 v86, v86
	v_exp_f32_e32 v87, v87
	v_exp_f32_e32 v88, v88
	v_exp_f32_e32 v89, v89
	v_mfma_f32_32x32x16_bf16 v[2:17], v[114:117], v[54:57], v[2:17]
	v_exp_f32_e32 v90, v90
	v_exp_f32_e32 v91, v91
	v_exp_f32_e32 v92, v92
	v_exp_f32_e32 v93, v93
	v_mfma_f32_32x32x16_bf16 v[18:33], v[114:117], v[58:61], v[18:33]
	v_exp_f32_e32 v94, v94
	v_exp_f32_e32 v95, v95
	v_exp_f32_e32 v96, v96
	v_exp_f32_e32 v97, v97
	s_waitcnt vmcnt(2) lgkmcnt(0)
	s_barrier
	s_andn2_b64 vcc, exec, s[4:5]
	s_cbranch_vccnz .LBB0_710
	s_waitcnt lgkmcnt(0)
	v_add_u32_e32 v66, s17, v203
	ds_read_b128 v[50:53], v66 offset:49248
	ds_read_b128 v[54:57], v66 offset:49216
	ds_read_b128 v[58:61], v66 offset:49184
	ds_read_b128 v[66:69], v66 offset:49152
	s_waitcnt lgkmcnt(3)
	v_pk_mul_f32 v[14:15], v[14:15], v[50:51]
	s_waitcnt lgkmcnt(2)
	v_pk_mul_f32 v[10:11], v[10:11], v[54:55]
	s_waitcnt lgkmcnt(1)
	v_pk_mul_f32 v[6:7], v[6:7], v[58:59]
	v_pk_mul_f32 v[16:17], v[16:17], v[52:53]
	v_pk_mul_f32 v[12:13], v[12:13], v[56:57]
	v_pk_mul_f32 v[8:9], v[8:9], v[60:61]
	s_waitcnt lgkmcnt(0)
	v_pk_mul_f32 v[4:5], v[4:5], v[68:69]
	v_pk_mul_f32 v[2:3], v[2:3], v[66:67]
	v_pk_mul_f32 v[30:31], v[30:31], v[50:51]
	v_pk_mul_f32 v[26:27], v[26:27], v[54:55]
	v_pk_mul_f32 v[22:23], v[22:23], v[58:59]
	v_pk_mul_f32 v[32:33], v[32:33], v[52:53]
	v_pk_mul_f32 v[28:29], v[28:29], v[56:57]
	v_pk_mul_f32 v[24:25], v[24:25], v[60:61]
	v_pk_mul_f32 v[20:21], v[20:21], v[68:69]
	v_pk_mul_f32 v[18:19], v[18:19], v[66:67]
.LBB0_710:
	s_add_i32 s4, s21, 0x2000
	s_cmpk_lg_i32 s21, 0x4000
	s_cselect_b32 s25, s4, 0
	v_add_u32_e32 v186, s24, v207
	ds_read_b64_tr_b16 v[150:151], v186 offset:24576
	ds_read_b64_tr_b16 v[152:153], v186 offset:25088
	v_mfma_f32_32x32x16_bf16 v[66:81], v[62:65], v[142:145], v[34:49]
	v_add_f32_e32 v50, v98, v99
	v_add_f32_e32 v50, v100, v50
	v_add_f32_e32 v50, v101, v50
	v_add_f32_e32 v50, v102, v50
	v_add_f32_e32 v50, v103, v50
	v_cvt_pk_bf16_f32 v134, v98, v99
	v_cvt_pk_bf16_f32 v135, v100, v101
	ds_read_b64_tr_b16 v[146:147], v186 offset:28672
	ds_read_b64_tr_b16 v[148:149], v186 offset:29184
	v_add_f32_e32 v50, v104, v50
	v_add_f32_e32 v50, v105, v50
	v_add_f32_e32 v50, v106, v50
	v_add_f32_e32 v114, v107, v50
	v_mfma_f32_32x32x16_bf16 v[50:65], v[174:177], v[142:145], v[34:49]
	v_cvt_pk_bf16_f32 v136, v102, v103
	v_cvt_pk_bf16_f32 v137, v104, v105
	ds_read_b64_tr_b16 v[98:99], v186 offset:25600
	ds_read_b64_tr_b16 v[100:101], v186 offset:26112
	v_mfma_f32_32x32x16_bf16 v[66:81], v[178:181], v[138:141], v[66:81]
	v_add_f32_e32 v102, v108, v114
	v_add_f32_e32 v102, v109, v102
	v_add_f32_e32 v102, v110, v102
	v_add_f32_e32 v114, v111, v102
	v_cvt_pk_bf16_f32 v126, v106, v107
	v_cvt_pk_bf16_f32 v127, v108, v109
	ds_read_b64_tr_b16 v[102:103], v186 offset:29696
	ds_read_b64_tr_b16 v[104:105], v186 offset:30208
	v_mfma_f32_32x32x16_bf16 v[50:65], v[170:173], v[138:141], v[50:65]
	v_add_f32_e32 v106, v112, v114
	v_add_f32_e32 v106, v113, v106
	v_add_f32_e32 v106, v82, v106
	v_add_f32_e32 v114, v83, v106
	v_cvt_pk_bf16_f32 v128, v110, v111
	v_cvt_pk_bf16_f32 v129, v112, v113
	ds_read_b64_tr_b16 v[106:107], v186 offset:26624
	ds_read_b64_tr_b16 v[108:109], v186 offset:27136
	v_mfma_f32_32x32x16_bf16 v[66:81], v[166:169], v[130:133], v[66:81]
	v_add_f32_e32 v110, v84, v114
	v_add_f32_e32 v110, v85, v110
	v_add_f32_e32 v110, v86, v110
	v_add_f32_e32 v110, v87, v110
	v_cvt_pk_bf16_f32 v118, v82, v83
	v_cvt_pk_bf16_f32 v119, v84, v85
	ds_read_b64_tr_b16 v[82:83], v186 offset:30720
	ds_read_b64_tr_b16 v[84:85], v186 offset:31232
	v_mfma_f32_32x32x16_bf16 v[50:65], v[162:165], v[130:133], v[50:65]
	v_add_f32_e32 v110, v88, v110
	v_add_f32_e32 v110, v89, v110
	v_add_f32_e32 v110, v90, v110
	v_add_f32_e32 v110, v91, v110
	v_cvt_pk_bf16_f32 v120, v86, v87
	v_cvt_pk_bf16_f32 v121, v88, v89
	ds_read_b64_tr_b16 v[86:87], v186 offset:27648
	ds_read_b64_tr_b16 v[88:89], v186 offset:28160
	v_mfma_f32_32x32x16_bf16 v[66:81], v[158:161], v[122:125], v[66:81]
	v_add_f32_e32 v110, v92, v110
	v_add_f32_e32 v110, v93, v110
	v_add_f32_e32 v110, v94, v110
	v_add_f32_e32 v110, v95, v110
	v_cvt_pk_bf16_f32 v114, v90, v91
	v_cvt_pk_bf16_f32 v115, v92, v93
	ds_read_b64_tr_b16 v[90:91], v186 offset:31744
	ds_read_b64_tr_b16 v[92:93], v186 offset:32256
	v_mfma_f32_32x32x16_bf16 v[50:65], v[154:157], v[122:125], v[50:65]
	v_add_f32_e32 v110, v96, v110
	v_add_f32_e32 v110, v97, v110
	v_cvt_pk_bf16_f32 v116, v94, v95
	v_cvt_pk_bf16_f32 v117, v96, v97
	s_cmpk_lt_u32 s22, 0x7c
	s_cselect_b32 s4, 0, 0xffffff80
	s_cselect_b32 s5, s9, s20
	s_add_i32 s4, s4, s23
	s_lshl_b32 s4, s4, 6
	s_add_i32 s4, s4, s5
	s_addk_i32 s4, 0x180
	s_add_i32 m0, s21, s18
	v_mad_i64_i32 v[94:95], s[4:5], s4, v217, v[192:193]
	global_load_lds_dwordx4 v[94:95], off
	v_lshl_add_u64 v[94:95], v[196:197], 0, s[30:31]
	s_add_i32 s4, s25, s19
	s_mov_b32 m0, s4
	s_nop 0
	global_load_lds_dwordx4 v[94:95], off
	v_max_f32_e32 v94, v66, v67
	v_max3_f32 v95, v68, v69, v51
	v_max3_f32 v94, v94, v50, v52
	v_max3_f32 v94, v94, v53, v70
	v_max3_f32 v95, v95, v72, v73
	v_max3_f32 v94, v94, v71, v54
	v_max3_f32 v95, v95, v56, v57
	v_max3_f32 v94, v94, v55, v74
	v_max3_f32 v95, v95, v76, v77
	v_max3_f32 v94, v94, v75, v58
	v_max3_f32 v95, v95, v60, v61
	v_max3_f32 v94, v94, v59, v78
	v_max3_f32 v95, v95, v80, v81
	v_max3_f32 v94, v94, v79, v62
	v_max3_f32 v95, v95, v64, v65
	v_max3_f32 v94, v94, v63, v95
	v_mov_b32_e32 v95, v94
	s_nop 1
	v_permlane32_swap_b32_e32 v94, v95
	v_max_f32_e32 v94, v94, v95
	v_cmp_lt_f32_e32 vcc, s51, v94
	s_cmp_lg_u64 vcc, 0
	v_add_f32_e32 v224, v224, v110
	s_cselect_b64 s[4:5], -1, 0
	s_cbranch_vccnz .LBB0_718
.LBB0_711:
	s_waitcnt lgkmcnt(0)
	v_mfma_f32_32x32x16_bf16 v[2:17], v[134:137], v[150:153], v[2:17]
	v_exp_f32_e32 v66, v66
	v_exp_f32_e32 v67, v67
	v_exp_f32_e32 v68, v68
	v_exp_f32_e32 v69, v69
	v_mfma_f32_32x32x16_bf16 v[18:33], v[134:137], v[146:149], v[18:33]
	v_exp_f32_e32 v70, v70
	v_exp_f32_e32 v71, v71
	v_exp_f32_e32 v72, v72
	v_exp_f32_e32 v73, v73
	v_add_u32_e32 v94, s25, v206
	ds_read_b128 v[174:177], v94
	ds_read_b128 v[170:173], v94 offset:512
	v_mfma_f32_32x32x16_bf16 v[2:17], v[126:129], v[98:101], v[2:17]
	v_exp_f32_e32 v74, v74
	v_exp_f32_e32 v75, v75
	v_exp_f32_e32 v76, v76
	v_exp_f32_e32 v77, v77
	ds_read_b128 v[166:169], v94 offset:2048
	ds_read_b128 v[162:165], v94 offset:2560
	v_mfma_f32_32x32x16_bf16 v[18:33], v[126:129], v[102:105], v[18:33]
	v_exp_f32_e32 v78, v78
	v_exp_f32_e32 v79, v79
	v_exp_f32_e32 v80, v80
	v_exp_f32_e32 v81, v81
	ds_read_b128 v[158:161], v94 offset:4096
	ds_read_b128 v[154:157], v94 offset:4608
	v_mfma_f32_32x32x16_bf16 v[2:17], v[118:121], v[106:109], v[2:17]
	v_exp_f32_e32 v50, v50
	v_exp_f32_e32 v51, v51
	v_exp_f32_e32 v52, v52
	v_exp_f32_e32 v53, v53
	ds_read_b128 v[150:153], v94 offset:6144
	ds_read_b128 v[146:149], v94 offset:6656
	v_mfma_f32_32x32x16_bf16 v[18:33], v[118:121], v[82:85], v[18:33]
	v_exp_f32_e32 v54, v54
	v_exp_f32_e32 v55, v55
	v_exp_f32_e32 v56, v56
	v_exp_f32_e32 v57, v57
	v_mfma_f32_32x32x16_bf16 v[2:17], v[114:117], v[86:89], v[2:17]
	v_exp_f32_e32 v58, v58
	v_exp_f32_e32 v59, v59
	v_exp_f32_e32 v60, v60
	v_exp_f32_e32 v61, v61
	v_mfma_f32_32x32x16_bf16 v[18:33], v[114:117], v[90:93], v[18:33]
	v_exp_f32_e32 v62, v62
	v_exp_f32_e32 v63, v63
	v_exp_f32_e32 v64, v64
	v_exp_f32_e32 v65, v65
	s_waitcnt vmcnt(2) lgkmcnt(0)
	s_barrier
	s_andn2_b64 vcc, exec, s[4:5]
	s_cbranch_vccnz .LBB0_713
	s_waitcnt lgkmcnt(0)
	v_add_u32_e32 v94, s17, v203
	ds_read_b128 v[82:85], v94 offset:49248
	ds_read_b128 v[86:89], v94 offset:49216
	ds_read_b128 v[90:93], v94 offset:49152
	ds_read_b128 v[94:97], v94 offset:49184
	s_waitcnt lgkmcnt(3)
	v_pk_mul_f32 v[16:17], v[16:17], v[84:85]
	v_pk_mul_f32 v[14:15], v[14:15], v[82:83]
	s_waitcnt lgkmcnt(2)
	v_pk_mul_f32 v[12:13], v[12:13], v[88:89]
	v_pk_mul_f32 v[10:11], v[10:11], v[86:87]
	s_waitcnt lgkmcnt(0)
	v_pk_mul_f32 v[8:9], v[8:9], v[96:97]
	v_pk_mul_f32 v[6:7], v[6:7], v[94:95]
	v_pk_mul_f32 v[4:5], v[4:5], v[92:93]
	v_pk_mul_f32 v[2:3], v[2:3], v[90:91]
	v_pk_mul_f32 v[32:33], v[32:33], v[84:85]
	v_pk_mul_f32 v[30:31], v[30:31], v[82:83]
	v_pk_mul_f32 v[28:29], v[28:29], v[88:89]
	v_pk_mul_f32 v[26:27], v[26:27], v[86:87]
	v_pk_mul_f32 v[24:25], v[24:25], v[96:97]
	v_pk_mul_f32 v[22:23], v[22:23], v[94:95]
	v_pk_mul_f32 v[20:21], v[20:21], v[92:93]
	v_pk_mul_f32 v[18:19], v[18:19], v[90:91]
